# combo: LDS-transposed retention epilogue + M1 epilogue shw/rowss prefetch one tile ahead + S5a C-fragment loads batched (on top of nt P0 loads)
# speedup vs baseline: 1.0138x; 1.0138x over previous
.LBB0_944:
	s_or_b64 exec, exec, s[10:11]
	s_waitcnt vmcnt(0)
	v_mul_f32_e32 v37, v26, v22
	v_mul_f32_e32 v38, 0x3fb8aa3b, v37
	s_mov_b32 s12, 0x3fb8aa3b
	v_fma_f32 v39, v37, s12, -v38
	v_rndne_f32_e32 v40, v38
	v_fmac_f32_e32 v39, 0x32a5705f, v37
	v_sub_f32_e32 v38, v38, v40
	v_add_f32_e32 v38, v38, v39
	v_exp_f32_e32 v38, v38
	v_cvt_i32_f32_e32 v39, v40
	s_mov_b32 s13, 0xc2ce8ed0
	v_cmp_ngt_f32_e32 vcc, s13, v37
	s_mov_b32 s15, 0x42b17218
	v_ldexp_f32 v38, v38, v39
	v_cndmask_b32_e32 v38, 0, v38, vcc
	v_cmp_nlt_f32_e32 vcc, s15, v37
	v_mov_b32_e32 v41, 0xbab64f3b
	v_mul_f32_e32 v26, v26, v20
	v_cndmask_b32_e32 v37, v253, v38, vcc
	v_mul_f32_e32 v38, v36, v36
	v_fmamk_f32 v39, v38, 0xb94c1982, v237
	v_fmaak_f32 v39, v38, v39, 0xbe2aaa9d
	v_mul_f32_e32 v39, v38, v39
	v_fmac_f32_e32 v36, v36, v39
	v_fmamk_f32 v39, v38, 0x37d75334, v41
	v_fmaak_f32 v39, v38, v39, 0x3d2aabf7
	v_fmaak_f32 v39, v38, v39, 0xbf000004
	v_fma_f32 v38, v38, v39, 1.0
	v_and_b32_e32 v39, 1, v35
	v_cmp_eq_u32_e32 vcc, 0, v39
	s_brev_b32 s16, 1
	s_movk_i32 s17, 0x1f8
	v_cndmask_b32_e64 v36, -v36, v38, vcc
	v_mul_f32_e32 v38, 0x3fb8aa3b, v26
	v_fma_f32 v39, v26, s12, -v38
	v_rndne_f32_e32 v40, v38
	v_fmac_f32_e32 v39, 0x32a5705f, v26
	v_sub_f32_e32 v38, v38, v40
	v_add_f32_e32 v38, v38, v39
	v_exp_f32_e32 v38, v38
	v_cvt_i32_f32_e32 v39, v40
	v_cmp_ngt_f32_e32 vcc, s13, v26
	v_mov_b32_e32 v42, 0x7fc00000
	v_lshlrev_b32_e32 v35, 30, v35
	v_ldexp_f32 v38, v38, v39
	v_cndmask_b32_e32 v38, 0, v38, vcc
	v_cmp_nlt_f32_e32 vcc, s15, v26
	v_bitop3_b32 v35, v35, v36, s16 bitop3:0x6c
	v_cmp_class_f32_e64 s[10:11], v29, s17
	v_cndmask_b32_e32 v26, v253, v38, vcc
	v_mul_f32_e32 v38, v28, v28
	v_fmamk_f32 v39, v38, 0xb94c1982, v237
	v_fmaak_f32 v39, v38, v39, 0xbe2aaa9d
	v_mul_f32_e32 v39, v38, v39
	v_fmac_f32_e32 v28, v28, v39
	v_fmamk_f32 v39, v38, 0x37d75334, v41
	v_fmaak_f32 v39, v38, v39, 0x3d2aabf7
	v_fmaak_f32 v39, v38, v39, 0xbf000004
	v_fma_f32 v38, v38, v39, 1.0
	v_and_b32_e32 v39, 1, v27
	v_cmp_eq_u32_e32 vcc, 0, v39
	v_lshlrev_b32_e32 v27, 30, v27
	v_cndmask_b32_e64 v35, v42, v35, s[10:11]
	v_cndmask_b32_e64 v28, -v28, v38, vcc
	v_bitop3_b32 v27, v27, v28, s16 bitop3:0x6c
	v_mul_f32_e32 v28, v32, v32
	v_fmamk_f32 v39, v28, 0xb94c1982, v237
	v_fmaak_f32 v39, v28, v39, 0xbe2aaa9d
	v_mul_f32_e32 v39, v28, v39
	v_fmac_f32_e32 v32, v32, v39
	v_fmamk_f32 v39, v28, 0x37d75334, v41
	v_fmaak_f32 v39, v28, v39, 0x3d2aabf7
	v_fmaak_f32 v39, v28, v39, 0xbf000004
	v_fma_f32 v28, v28, v39, 1.0
	v_and_b32_e32 v39, 1, v31
	v_lshlrev_b32_e32 v31, 30, v31
	v_cmp_class_f32_e64 vcc, v24, s17
	v_cmp_eq_u32_e64 s[12:13], 0, v39
	v_and_b32_e32 v31, 0x80000000, v31
	v_xor_b32_e32 v24, v25, v24
	v_cndmask_b32_e64 v28, v28, v32, s[12:13]
	v_xor_b32_e32 v24, v24, v31
	v_xor_b32_e32 v24, v24, v28
	v_cndmask_b32_e32 v27, v42, v27, vcc
	v_cndmask_b32_e32 v24, v42, v24, vcc
	v_mul_f32_e32 v25, v26, v24
	v_fma_f32 v24, v26, v27, -1.0
	v_mul_f32_e32 v38, v26, v27
	v_pk_mul_f32 v[26:27], v[20:21], v[24:25]
	v_mov_b32_e32 v28, v21
	v_add_f32_e32 v31, v26, v27
	v_mov_b32_e32 v26, v25
	v_mov_b32_e32 v27, v20
	v_pk_mul_f32 v[26:27], v[20:21], v[26:27] op_sel_hi:[0,1]
	v_mov_b32_e32 v20, v24
	v_pk_mul_f32 v[20:21], v[28:29], v[20:21] op_sel_hi:[0,1]
	v_add_f32_e32 v21, v27, v21
	v_div_scale_f32 v24, s[12:13], v21, v21, v31
	v_rcp_f32_e32 v27, v24
	v_sub_f32_e32 v20, v26, v20
	v_div_scale_f32 v26, s[12:13], v21, v21, v20
	v_fma_f32 v28, -v24, v27, 1.0
	v_fmac_f32_e32 v27, v28, v27
	v_div_scale_f32 v28, vcc, v31, v21, v31
	v_mul_f32_e32 v32, v28, v27
	v_fma_f32 v39, -v24, v32, v28
	v_fmac_f32_e32 v32, v39, v27
	v_fma_f32 v24, -v24, v32, v28
	v_div_fmas_f32 v24, v24, v27, v32
	v_rcp_f32_e32 v27, v26
	v_div_fixup_f32 v24, v24, v21, v31
	s_lshl_b64 s[38:39], s[96:97], 12
	s_movk_i32 s13, 0x98
	v_fma_f32 v28, -v26, v27, 1.0
	v_fmac_f32_e32 v27, v28, v27
	v_div_scale_f32 v28, vcc, v20, v21, v20
	v_mul_f32_e32 v31, v28, v27
	v_fma_f32 v32, -v26, v31, v28
	v_fmac_f32_e32 v31, v32, v27
	v_fma_f32 v26, -v26, v31, v28
	v_div_fmas_f32 v26, v26, v27, v31
	v_div_fixup_f32 v20, v26, v21, v20
	v_pk_mul_f32 v[26:27], v[12:13], v[20:21] op_sel_hi:[1,0]
	s_ashr_i32 s12, s36, 6
	v_pk_fma_f32 v[26:27], v[8:9], v[24:25], v[26:27] op_sel_hi:[1,0,1] neg_lo:[0,0,1] neg_hi:[0,0,1]
	v_pk_mul_f32 v[8:9], v[8:9], v[20:21] op_sel_hi:[1,0]
	s_lshl_b32 s96, s37, 5
	v_pk_fma_f32 v[8:9], v[12:13], v[24:25], v[8:9] op_sel_hi:[1,0,1]
	v_mul_f32_e32 v36, v37, v35
	v_cvt_pk_bf16_f32 v52, v8, v9
	v_pk_mul_f32 v[8:9], v[14:15], v[20:21] op_sel_hi:[1,0]
	v_mov_b32_e32 v110, 0
	v_pk_fma_f32 v[8:9], v[10:11], v[24:25], v[8:9] op_sel_hi:[1,0,1] neg_lo:[0,0,1] neg_hi:[0,0,1]
	v_cndmask_b32_e64 v108, v38, v36, s[6:7]
	v_cvt_pk_bf16_f32 v49, v8, v9
	v_pk_mul_f32 v[8:9], v[10:11], v[20:21] op_sel_hi:[1,0]
	v_lshl_add_u64 v[112:113], v[100:101], 0, s[96:97]
	v_pk_fma_f32 v[8:9], v[14:15], v[24:25], v[8:9] op_sel_hi:[1,0,1]
	s_mov_b32 s14, 0
	v_cvt_pk_bf16_f32 v53, v8, v9
	v_pk_mul_f32 v[8:9], v[4:5], v[20:21] op_sel_hi:[1,0]
	v_cvt_pk_bf16_f32 v48, v26, v27
	v_pk_fma_f32 v[8:9], v[0:1], v[24:25], v[8:9] op_sel_hi:[1,0,1] neg_lo:[0,0,1] neg_hi:[0,0,1]
	v_pk_mul_f32 v[0:1], v[0:1], v[20:21] op_sel_hi:[1,0]
	v_cvt_pk_bf16_f32 v50, v8, v9
	v_pk_fma_f32 v[0:1], v[4:5], v[24:25], v[0:1] op_sel_hi:[1,0,1]
	v_xor_b32_e32 v4, v30, v29
	v_cvt_pk_bf16_f32 v54, v0, v1
	v_pk_mul_f32 v[0:1], v[6:7], v[20:21] op_sel_hi:[1,0]
	v_mov_b32_e32 v109, v108
	v_pk_fma_f32 v[0:1], v[2:3], v[24:25], v[0:1] op_sel_hi:[1,0,1] neg_lo:[0,0,1] neg_hi:[0,0,1]
	v_mov_b32_e32 v111, v110
	v_cvt_pk_bf16_f32 v51, v0, v1
	v_pk_mul_f32 v[0:1], v[2:3], v[20:21] op_sel_hi:[1,0]
	v_mul_f32_e32 v2, v34, v34
	v_fmamk_f32 v3, v2, 0xb94c1982, v237
	v_fmaak_f32 v3, v2, v3, 0xbe2aaa9d
	v_mul_f32_e32 v3, v2, v3
	v_fmac_f32_e32 v34, v34, v3
	v_fmamk_f32 v3, v2, 0x37d75334, v41
	v_fmaak_f32 v3, v2, v3, 0x3d2aabf7
	v_fmaak_f32 v3, v2, v3, 0xbf000004
	v_fma_f32 v2, v2, v3, 1.0
	v_and_b32_e32 v3, 1, v33
	v_cmp_eq_u32_e32 vcc, 0, v3
	v_lshlrev_b32_e32 v3, 30, v33
	v_and_b32_e32 v3, 0x80000000, v3
	v_cndmask_b32_e32 v2, v2, v34, vcc
	v_xor_b32_e32 v3, v4, v3
	v_xor_b32_e32 v2, v3, v2
	v_cndmask_b32_e64 v2, v42, v2, s[10:11]
	v_mul_f32_e32 v3, v37, v2
	v_fma_f32 v2, v37, v35, -1.0
	v_pk_mul_f32 v[4:5], v[22:23], v[2:3]
	v_pk_fma_f32 v[0:1], v[6:7], v[24:25], v[0:1] op_sel_hi:[1,0,1]
	v_cndmask_b32_e64 v107, v25, v3, s[6:7]
	v_add_f32_e32 v7, v4, v5
	v_mov_b32_e32 v4, v3
	v_mov_b32_e32 v5, v22
	v_mov_b32_e32 v6, v23
	v_mov_b32_e32 v3, v23
	v_pk_mul_f32 v[4:5], v[22:23], v[4:5] op_sel_hi:[0,1]
	v_pk_mul_f32 v[2:3], v[6:7], v[2:3] op_sel_hi:[0,1]
	v_add_f32_e32 v3, v5, v3
	v_div_scale_f32 v5, s[10:11], v3, v3, v7
	v_rcp_f32_e32 v6, v5
	v_sub_f32_e32 v2, v4, v2
	v_div_scale_f32 v4, s[10:11], v3, v3, v2
	v_fma_f32 v8, -v5, v6, 1.0
	v_fmac_f32_e32 v6, v8, v6
	v_div_scale_f32 v8, vcc, v7, v3, v7
	v_mul_f32_e32 v9, v8, v6
	v_fma_f32 v10, -v5, v9, v8
	v_fmac_f32_e32 v9, v10, v6
	v_fma_f32 v5, -v5, v9, v8
	v_div_fmas_f32 v5, v5, v6, v9
	v_div_fixup_f32 v20, v5, v3, v7
	v_rcp_f32_e32 v5, v4
	v_cvt_pk_bf16_f32 v55, v0, v1
	v_mov_b32_e32 v1, s77
	v_or_b32_e32 v0, s76, v94
	v_fma_f32 v6, -v4, v5, 1.0
	v_fmac_f32_e32 v5, v6, v5
	v_div_scale_f32 v6, vcc, v2, v3, v2
	v_mul_f32_e32 v7, v6, v5
	v_fma_f32 v8, -v4, v7, v6
	v_fmac_f32_e32 v7, v8, v5
	v_fma_f32 v4, -v4, v7, v6
	v_div_fmas_f32 v4, v4, v5, v7
	v_lshlrev_b64 v[0:1], 6, v[0:1]
	v_div_fixup_f32 v22, v4, v3, v2
	v_lshl_add_u64 v[4:5], v[16:17], 0, v[0:1]
	v_lshl_add_u64 v[12:13], v[18:19], 0, v[0:1]
	global_load_dwordx4 v[0:3], v[4:5], off offset:16
	s_nop 0
	global_load_dwordx4 v[4:7], v[4:5], off
	s_nop 0
	global_load_dwordx4 v[8:11], v[12:13], off offset:16
	s_nop 0
	global_load_dwordx4 v[12:15], v[12:13], off
	s_movk_i32 s10, 0x90
	s_load_dwordx2 s[10:11], s[4:5], s10
	s_waitcnt lgkmcnt(0)
	s_load_dwordx2 s[16:17], s[4:5], s13
	s_waitcnt lgkmcnt(0)
	v_xor_b32_e32 v106, 0x80000000, v107
	s_waitcnt vmcnt(0)
	v_pk_mul_f32 v[16:17], v[12:13], v[22:23] op_sel_hi:[1,0]
	s_nop 0
	v_pk_fma_f32 v[16:17], v[4:5], v[20:21], v[16:17] op_sel_hi:[1,0,1] neg_lo:[0,0,1] neg_hi:[0,0,1]
	v_pk_mul_f32 v[4:5], v[4:5], v[22:23] op_sel_hi:[1,0]
	v_cvt_pk_bf16_f32 v56, v16, v17
	v_pk_fma_f32 v[4:5], v[12:13], v[20:21], v[4:5] op_sel_hi:[1,0,1]
	s_nop 0
	v_cvt_pk_bf16_f32 v60, v4, v5
	v_pk_mul_f32 v[4:5], v[14:15], v[22:23] op_sel_hi:[1,0]
	s_nop 0
	v_pk_fma_f32 v[4:5], v[6:7], v[20:21], v[4:5] op_sel_hi:[1,0,1] neg_lo:[0,0,1] neg_hi:[0,0,1]
	s_nop 0
	v_cvt_pk_bf16_f32 v57, v4, v5
	v_pk_mul_f32 v[4:5], v[6:7], v[22:23] op_sel_hi:[1,0]
	s_nop 0
	v_pk_fma_f32 v[4:5], v[14:15], v[20:21], v[4:5] op_sel_hi:[1,0,1]
	s_nop 0
	v_cvt_pk_bf16_f32 v61, v4, v5
	v_pk_mul_f32 v[4:5], v[8:9], v[22:23] op_sel_hi:[1,0]
	s_nop 0
	v_pk_fma_f32 v[4:5], v[0:1], v[20:21], v[4:5] op_sel_hi:[1,0,1] neg_lo:[0,0,1] neg_hi:[0,0,1]
	v_pk_mul_f32 v[0:1], v[0:1], v[22:23] op_sel_hi:[1,0]
	v_cvt_pk_bf16_f32 v58, v4, v5
	v_pk_fma_f32 v[0:1], v[8:9], v[20:21], v[0:1] op_sel_hi:[1,0,1]
	s_nop 0
	v_cvt_pk_bf16_f32 v62, v0, v1
	v_pk_mul_f32 v[0:1], v[10:11], v[22:23] op_sel_hi:[1,0]
	s_nop 0
	v_pk_fma_f32 v[0:1], v[2:3], v[20:21], v[0:1] op_sel_hi:[1,0,1] neg_lo:[0,0,1] neg_hi:[0,0,1]
	s_nop 0
	v_cvt_pk_bf16_f32 v59, v0, v1
	v_pk_mul_f32 v[0:1], v[2:3], v[22:23] op_sel_hi:[1,0]
	s_nop 0
	v_pk_fma_f32 v[0:1], v[10:11], v[20:21], v[0:1] op_sel_hi:[1,0,1]
	v_lshlrev_b64 v[10:11], 2, v[96:97]
	v_cvt_pk_bf16_f32 v63, v0, v1
	v_lshl_or_b32 v0, v98, 2, s38
	v_mov_b32_e32 v1, s39
	v_lshl_add_u64 v[2:3], s[10:11], 0, v[0:1]
	v_lshl_add_u64 v[8:9], s[16:17], 0, v[0:1]
	v_lshl_add_u64 v[0:1], v[2:3], 0, v[10:11]
	v_lshl_add_u64 v[2:3], v[8:9], 0, v[10:11]
	global_load_dwordx4 v[12:15], v[0:1], off
	global_load_dwordx4 v[16:19], v[2:3], off
	global_load_dwordx4 v[20:23], v[0:1], off offset:64
	global_load_dwordx4 v[24:27], v[2:3], off offset:64
	global_load_dwordx4 v[28:31], v[0:1], off offset:128
	global_load_dwordx4 v[32:35], v[2:3], off offset:128
	global_load_dwordx4 v[36:39], v[0:1], off offset:192
	global_load_dwordx4 v[40:43], v[2:3], off offset:192
	s_lshl_b32 s10, s12, 8
	s_lshl_b32 s11, s37, 4
	v_or_b32_e32 v0, s10, v117
	v_ashrrev_i32_e32 v1, 31, v0
	v_lshlrev_b64 v[0:1], 12, v[0:1]
	v_lshl_add_u64 v[0:1], s[24:25], 0, v[0:1]
	v_lshl_add_u64 v[0:1], v[0:1], 0, s[96:97]
	v_lshl_add_u64 v[0:1], v[92:93], 1, v[0:1]
	global_load_dwordx4 v[84:87], v[0:1], off
	s_lshl_b32 s96, s37, 6
	v_lshl_add_u64 v[114:115], v[102:103], 0, s[96:97]
	s_waitcnt vmcnt(8)
	v_cvt_pk_bf16_f32 v4, v12, v13
	s_waitcnt vmcnt(7)
	v_cvt_pk_bf16_f32 v8, -v16, s0
	v_perm_b32 v64, v8, v4, s0
	v_cvt_pk_bf16_f32 v4, v13, s0
	v_cvt_pk_bf16_f32 v5, -v17, s0
	v_perm_b32 v65, v5, v4, s0
	v_cvt_pk_bf16_f32 v4, v14, v15
	v_cvt_pk_bf16_f32 v5, -v18, s0
	v_perm_b32 v66, v5, v4, s0
	v_cvt_pk_bf16_f32 v4, v15, s0
	v_cvt_pk_bf16_f32 v5, -v19, s0
	v_perm_b32 v67, v5, v4, s0
	s_waitcnt vmcnt(6)
	v_cvt_pk_bf16_f32 v4, v20, v21
	s_waitcnt vmcnt(5)
	v_cvt_pk_bf16_f32 v8, -v24, s0
	v_perm_b32 v68, v8, v4, s0
	v_cvt_pk_bf16_f32 v4, v21, s0
	v_cvt_pk_bf16_f32 v5, -v25, s0
	v_perm_b32 v69, v5, v4, s0
	v_cvt_pk_bf16_f32 v4, v22, v23
	v_cvt_pk_bf16_f32 v5, -v26, s0
	v_perm_b32 v70, v5, v4, s0
	v_cvt_pk_bf16_f32 v4, v23, s0
	v_cvt_pk_bf16_f32 v5, -v27, s0
	v_perm_b32 v71, v5, v4, s0
	s_waitcnt vmcnt(4)
	v_cvt_pk_bf16_f32 v4, v28, v29
	s_waitcnt vmcnt(3)
	v_cvt_pk_bf16_f32 v8, -v32, s0
	v_perm_b32 v72, v8, v4, s0
	v_cvt_pk_bf16_f32 v4, v29, s0
	v_cvt_pk_bf16_f32 v5, -v33, s0
	v_perm_b32 v73, v5, v4, s0
	v_cvt_pk_bf16_f32 v4, v30, v31
	v_cvt_pk_bf16_f32 v5, -v34, s0
	v_perm_b32 v74, v5, v4, s0
	v_cvt_pk_bf16_f32 v4, v31, s0
	v_cvt_pk_bf16_f32 v5, -v35, s0
	v_perm_b32 v75, v5, v4, s0
	s_waitcnt vmcnt(2)
	v_cvt_pk_bf16_f32 v4, v36, v37
	s_waitcnt vmcnt(1)
	v_cvt_pk_bf16_f32 v8, -v40, s0
	v_perm_b32 v76, v8, v4, s0
	v_cvt_pk_bf16_f32 v4, v37, s0
	v_cvt_pk_bf16_f32 v5, -v41, s0
	v_perm_b32 v77, v5, v4, s0
	v_cvt_pk_bf16_f32 v4, v38, v39
	v_cvt_pk_bf16_f32 v5, -v42, s0
	v_perm_b32 v78, v5, v4, s0
	v_cvt_pk_bf16_f32 v4, v39, s0
	v_cvt_pk_bf16_f32 v5, -v43, s0
	v_perm_b32 v79, v5, v4, s0
	s_waitcnt vmcnt(0)
	v_mov_b64_e32 v[80:81], v[84:85]
	v_mov_b64_e32 v[82:83], v[86:87]

.LBB0_1294:
	v_readlane_b32 s12, v255, 44
	s_lshl_b32 s12, s12, 1
	v_readlane_b32 s13, v255, 45
	s_or_b32 s96, s12, 1
	s_lshl_b64 s[12:13], s[96:97], 16
	v_readlane_b32 s14, v254, 11
	s_add_u32 s12, s14, s12
	v_readlane_b32 s14, v254, 14
	s_addc_u32 s13, s14, s13
	s_mul_i32 s15, s96, 0x1e000
	v_readlane_b32 s19, v254, 7
	s_mul_hi_u32 s14, s96, 0x1e000
	s_add_u32 s51, s19, s15
	v_readlane_b32 s15, v254, 8
	s_addc_u32 s76, s15, s14
	s_add_u32 s14, s6, 0x9900000
	s_addc_u32 s15, s7, 0
	s_lshl_b32 s6, s18, 5
	s_and_b32 s18, s6, 0x60
	s_add_i32 m0, s37, 0x18000
	v_lshl_add_u64 v[6:7], v[6:7], 0, s[20:21]
	s_lshl_b32 s19, s17, 13
	s_lshl_b32 s22, s18, 7
	s_waitcnt vmcnt(2)
	s_barrier
	global_load_lds_dwordx4 v[6:7], off
	v_lshl_add_u64 v[4:5], v[4:5], 0, s[20:21]
	s_add_i32 m0, s37, 0x1a000
	s_add_i32 s77, s37, 0x8000
	s_add_i32 s78, s37, 0xa000
	global_load_lds_dwordx4 v[4:5], off
	v_lshl_add_u64 v[0:1], v[0:1], 0, s[20:21]
	s_mov_b32 m0, s77
	s_add_u32 s6, s52, 0x40080
	global_load_lds_dwordx4 v[0:1], off
	v_lshl_add_u64 v[0:1], v[2:3], 0, s[20:21]
	s_mov_b32 m0, s78
	s_addc_u32 s7, s53, 0
	global_load_lds_dwordx4 v[0:1], off
	s_add_i32 m0, s37, 0x1c000
	v_lshl_add_u64 v[0:1], s[6:7], 0, v[200:201]
	global_load_lds_dwordx4 v[0:1], off
	v_lshl_add_u64 v[0:1], s[6:7], 0, v[144:145]
	s_add_i32 m0, s37, 0x1e000
	s_cmpk_lt_u32 s16, 0x100
	global_load_lds_dwordx4 v[0:1], off
	v_lshrrev_b32_e32 v1, 1, v8
	v_and_b32_e32 v1, 24, v1
	v_and_b32_e32 v0, 15, v8
	v_lshlrev_b32_e32 v2, 1, v1
	v_lshl_or_b32 v162, s17, 6, v0
	v_lshl_or_b32 v0, v0, 6, v2
	v_lshlrev_b32_e32 v2, 2, v8
	v_and_b32_e32 v2, 32, v2
	v_bitop3_b32 v3, v0, s19, v2 bitop3:0xde
	v_bitop3_b32 v163, s22, v0, v2 bitop3:0xf6
	v_lshlrev_b32_e32 v0, 14, v13
	v_and_b32_e32 v0, 0xffff8000, v0
	v_or_b32_e32 v164, s18, v1
	v_lshl_add_u32 v0, v12, 11, v0
	v_and_b32_e32 v1, 1, v13
	v_lshl_or_b32 v0, v1, 6, v0
	v_lshl_add_u32 v150, v14, 1, v0
	v_lshlrev_b32_e32 v0, 14, v9
	v_and_b32_e32 v0, 0xffff8000, v0
	s_waitcnt vmcnt(6)
	v_lshl_add_u32 v0, v10, 11, v0
	v_and_b32_e32 v1, 1, v9
	v_lshl_or_b32 v0, v1, 6, v0
	v_readlane_b32 s6, v255, 14
	s_cselect_b64 s[16:17], -1, 0
	v_mov_b32_e32 v151, v201
	v_lshl_add_u32 v152, v11, 1, v0
	v_mov_b32_e32 v153, v201
	s_mov_b32 s79, 0
	v_add_u32_e32 v165, 0, v3
	v_readlane_b32 s41, v254, 56
	s_mov_b32 s40, s6
	s_barrier
	v_readlane_b32 s7, v255, 15
	s_lshl_b32 s92, s40, 8
	s_add_i32 s94, s92, 0xffffe000
	s_lshr_b32 s94, s94, 11
	s_add_i32 s94, s94, 1
	s_cmp_gt_i32 s40, 31
	s_cselect_b32 s94, s94, 0
	s_mul_hi_u32 s95, s94, 0x6000
	s_mulk_i32 s94, 0x6000
	v_lshl_or_b32 v226, s41, 8, v164
	s_add_u32 s94, s51, s94
	v_add_u32_e32 v188, s92, v162
	s_addc_u32 s95, s76, s95
	v_ashrrev_i32_e32 v227, 31, v226
	v_ashrrev_i32_e32 v189, 31, v188
	v_lshl_add_u64 v[226:227], v[226:227], 2, s[94:95]
	v_lshl_add_u64 v[188:189], v[188:189], 2, s[12:13]
	global_load_dword v242, v[188:189], off
	global_load_dword v243, v[188:189], off offset:64
	global_load_dword v244, v[188:189], off offset:128
	global_load_dword v245, v[188:189], off offset:192
	global_load_dword v246, v[188:189], off offset:512
	global_load_dword v247, v[188:189], off offset:576
	global_load_dword v248, v[188:189], off offset:640
	global_load_dword v249, v[188:189], off offset:704
	global_load_dwordx4 v[218:221], v[226:227], off offset:16
	global_load_dwordx4 v[222:225], v[226:227], off
	global_load_dwordx4 v[230:233], v[226:227], off offset:528
	global_load_dwordx4 v[238:241], v[226:227], off offset:512
	s_branch .LBB0_1297

.LBB0_1307:
	s_lshl_b32 s19, s40, 8
	s_add_i32 s8, s19, 0xffffe000
	s_lshr_b32 s8, s8, 11
	s_add_i32 s8, s8, 1
	s_cmp_gt_i32 s40, 31
	s_cselect_b32 s8, s8, 0
	s_mul_hi_u32 s9, s8, 0x6000
	s_mulk_i32 s8, 0x6000
	v_lshl_or_b32 v154, s41, 8, v164
	s_add_u32 s8, s51, s8
	v_add_u32_e32 v158, s19, v162
	s_addc_u32 s9, s76, s9
	v_ashrrev_i32_e32 v155, 31, v154
	v_ashrrev_i32_e32 v159, 31, v158
	v_lshl_add_u64 v[84:85], v[154:155], 2, s[8:9]
	v_lshl_add_u64 v[174:175], v[158:159], 2, s[12:13]
	v_mov_b32_e32 v88, v218
	v_mov_b32_e32 v89, v219
	v_mov_b32_e32 v90, v220
	v_mov_b32_e32 v91, v221
	v_mov_b32_e32 v92, v222
	v_mov_b32_e32 v93, v223
	v_mov_b32_e32 v94, v224
	v_mov_b32_e32 v95, v225
	v_mov_b32_e32 v80, v230
	v_mov_b32_e32 v81, v231
	v_mov_b32_e32 v82, v232
	v_mov_b32_e32 v83, v233
	s_nop 0
	v_mov_b32_e32 v84, v238
	v_mov_b32_e32 v85, v239
	v_mov_b32_e32 v86, v240
	v_mov_b32_e32 v87, v241
	v_or_b32_e32 v176, 16, v158
	v_mov_b32_e32 v173, v242
	v_mov_b32_e32 v172, v243
	v_mov_b32_e32 v171, v244
	v_or_b32_e32 v160, 32, v158
	v_or_b32_e32 v156, 48, v158
	v_lshlrev_b64 v[158:159], 13, v[158:159]
	v_mov_b32_e32 v170, v245
	v_mov_b32_e32 v169, v246
	v_mov_b32_e32 v168, v247
	v_mov_b32_e32 v167, v248
	v_mov_b32_e32 v166, v249
	v_lshl_add_u64 v[174:175], s[14:15], 0, v[158:159]
	v_lshlrev_b64 v[158:159], 1, v[154:155]
	v_lshl_add_u64 v[154:155], v[174:175], 0, v[158:159]
	v_ashrrev_i32_e32 v177, 31, v176
	v_ashrrev_i32_e32 v161, 31, v160
	v_ashrrev_i32_e32 v157, 31, v156
	s_waitcnt vmcnt(16)
	s_cmp_lg_u64 s[6:7], 0
	s_cbranch_scc0 .Lpf_skip
	s_lshl_b32 s92, s22, 8
	s_add_i32 s94, s92, 0xffffe000
	s_lshr_b32 s94, s94, 11
	s_add_i32 s94, s94, 1
	s_cmp_gt_i32 s22, 31
	s_cselect_b32 s94, s94, 0
	s_mul_hi_u32 s95, s94, 0x6000
	s_mulk_i32 s94, 0x6000
	v_lshl_or_b32 v226, s18, 8, v164
	s_add_u32 s94, s51, s94
	v_add_u32_e32 v188, s92, v162
	s_addc_u32 s95, s76, s95
	v_ashrrev_i32_e32 v227, 31, v226
	v_ashrrev_i32_e32 v189, 31, v188
	v_lshl_add_u64 v[226:227], v[226:227], 2, s[94:95]
	v_lshl_add_u64 v[188:189], v[188:189], 2, s[12:13]
	global_load_dword v242, v[188:189], off
	global_load_dword v243, v[188:189], off offset:64
	global_load_dword v244, v[188:189], off offset:128
	global_load_dword v245, v[188:189], off offset:192
	global_load_dword v246, v[188:189], off offset:512
	global_load_dword v247, v[188:189], off offset:576
	global_load_dword v248, v[188:189], off offset:640
	global_load_dword v249, v[188:189], off offset:704
	global_load_dwordx4 v[218:221], v[226:227], off offset:16
	global_load_dwordx4 v[222:225], v[226:227], off
	global_load_dwordx4 v[230:233], v[226:227], off offset:528
	global_load_dwordx4 v[238:241], v[226:227], off offset:512
.Lpf_skip:
	v_fmamk_f32 v173, v173, 0x3a800000, v228
	v_cmp_gt_f32_e32 vcc, s1, v173
	v_mul_f32_e32 v174, 0x4f800000, v173
	s_nop 0
	v_cndmask_b32_e32 v173, v173, v174, vcc
	v_sqrt_f32_e32 v174, v173
	s_nop 0
	v_add_u32_e32 v175, -1, v174
	v_fma_f32 v178, -v175, v174, v173
	v_cmp_ge_f32_e64 s[8:9], 0, v178
	v_add_u32_e32 v178, 1, v174
	s_nop 0
	v_cndmask_b32_e64 v175, v174, v175, s[8:9]
	v_fma_f32 v174, -v178, v174, v173
	v_cmp_lt_f32_e64 s[8:9], 0, v174
	s_nop 1
	v_cndmask_b32_e64 v174, v175, v178, s[8:9]
	v_mul_f32_e32 v175, 0x37800000, v174
	v_cndmask_b32_e32 v174, v174, v175, vcc
	v_cmp_class_f32_e32 vcc, v173, v229
	s_nop 1
	v_cndmask_b32_e32 v173, v174, v173, vcc
	v_div_scale_f32 v174, s[8:9], v173, v173, 1.0
	v_rcp_f32_e32 v175, v174
	s_nop 0
	v_fma_f32 v178, -v174, v175, 1.0
	v_fmac_f32_e32 v175, v178, v175
	v_div_scale_f32 v178, vcc, 1.0, v173, 1.0
	v_mul_f32_e32 v179, v178, v175
	v_fma_f32 v180, -v174, v179, v178
	v_fmac_f32_e32 v179, v180, v175
	v_fma_f32 v174, -v174, v179, v178
	v_div_fmas_f32 v174, v174, v175, v179
	v_div_fixup_f32 v174, v174, v173, 1.0
	v_pk_fma_f32 v[136:137], v[136:137], v[174:175], v[88:89] op_sel_hi:[1,0,1]
	v_pk_fma_f32 v[142:143], v[142:143], v[174:175], v[94:95] op_sel_hi:[1,0,1]
	v_pk_fma_f32 v[140:141], v[140:141], v[174:175], v[92:93] op_sel_hi:[1,0,1]
	v_pk_fma_f32 v[138:139], v[138:139], v[174:175], v[90:91] op_sel_hi:[1,0,1]
	v_max_f32_e32 v136, 0, v136
	v_max_f32_e32 v137, 0, v137
	v_max_f32_e32 v140, 0, v140
	v_max_f32_e32 v141, 0, v141
	v_pk_mul_f32 v[178:179], v[136:137], v[136:137]
	v_max_f32_e32 v136, 0, v142
	v_max_f32_e32 v138, 0, v138
	v_max_f32_e32 v137, 0, v143
	v_max_f32_e32 v139, 0, v139
	v_pk_mul_f32 v[140:141], v[140:141], v[140:141]
	v_pk_mul_f32 v[142:143], v[136:137], v[136:137]
	v_pk_mul_f32 v[180:181], v[138:139], v[138:139]
	v_pk_fma_f32 v[128:129], v[128:129], v[174:175], v[80:81] op_sel_hi:[1,0,1]
	v_cvt_pk_bf16_f32 v136, v140, v141
	v_cvt_pk_bf16_f32 v137, v142, v143
	v_cvt_pk_bf16_f32 v138, v178, v179
	v_cvt_pk_bf16_f32 v139, v180, v181
	v_pk_fma_f32 v[134:135], v[134:135], v[174:175], v[86:87] op_sel_hi:[1,0,1]
	v_pk_fma_f32 v[132:133], v[132:133], v[174:175], v[84:85] op_sel_hi:[1,0,1]
	v_pk_fma_f32 v[130:131], v[130:131], v[174:175], v[82:83] op_sel_hi:[1,0,1]
	v_max_f32_e32 v128, 0, v128
	v_max_f32_e32 v129, 0, v129
	global_store_dwordx4 v[154:155], v[136:139], off
	v_max_f32_e32 v132, 0, v132
	v_max_f32_e32 v133, 0, v133
	v_pk_mul_f32 v[136:137], v[128:129], v[128:129]
	v_max_f32_e32 v128, 0, v134
	v_max_f32_e32 v130, 0, v130
	v_max_f32_e32 v129, 0, v135
	v_max_f32_e32 v131, 0, v131
	v_pk_mul_f32 v[132:133], v[132:133], v[132:133]
	v_pk_mul_f32 v[134:135], v[128:129], v[128:129]
	v_pk_mul_f32 v[138:139], v[130:131], v[130:131]
	v_cvt_pk_bf16_f32 v128, v132, v133
	v_cvt_pk_bf16_f32 v129, v134, v135
	v_cvt_pk_bf16_f32 v130, v136, v137
	v_cvt_pk_bf16_f32 v131, v138, v139
	global_store_dwordx4 v[154:155], v[128:131], off offset:256
	s_nop 1
	v_fmamk_f32 v130, v172, 0x3a800000, v228
	v_cmp_gt_f32_e32 vcc, s1, v130
	v_mul_f32_e32 v131, 0x4f800000, v130
	v_lshlrev_b64 v[128:129], 13, v[176:177]
	v_cndmask_b32_e32 v130, v130, v131, vcc
	v_sqrt_f32_e32 v131, v130
	v_lshl_add_u64 v[128:129], s[14:15], 0, v[128:129]
	v_lshl_add_u64 v[128:129], v[128:129], 0, v[158:159]
	v_add_u32_e32 v132, -1, v131
	v_fma_f32 v133, -v132, v131, v130
	v_cmp_ge_f32_e64 s[8:9], 0, v133
	v_add_u32_e32 v133, 1, v131
	s_nop 0
	v_cndmask_b32_e64 v132, v131, v132, s[8:9]
	v_fma_f32 v131, -v133, v131, v130
	v_cmp_lt_f32_e64 s[8:9], 0, v131
	s_nop 1
	v_cndmask_b32_e64 v131, v132, v133, s[8:9]
	v_mul_f32_e32 v132, 0x37800000, v131
	v_cndmask_b32_e32 v131, v131, v132, vcc
	v_cmp_class_f32_e32 vcc, v130, v229
	s_nop 1
	v_cndmask_b32_e32 v130, v131, v130, vcc
	v_div_scale_f32 v131, s[8:9], v130, v130, 1.0
	v_rcp_f32_e32 v132, v131
	s_nop 0
	v_fma_f32 v133, -v131, v132, 1.0
	v_fmac_f32_e32 v132, v133, v132
	v_div_scale_f32 v133, vcc, 1.0, v130, 1.0
	v_mul_f32_e32 v134, v133, v132
	v_fma_f32 v135, -v131, v134, v133
	v_fmac_f32_e32 v134, v135, v132
	v_fma_f32 v131, -v131, v134, v133
	v_div_fmas_f32 v131, v131, v132, v134
	v_div_fixup_f32 v130, v131, v130, 1.0
	v_pk_fma_f32 v[120:121], v[120:121], v[130:131], v[88:89] op_sel_hi:[1,0,1]
	v_pk_fma_f32 v[126:127], v[126:127], v[130:131], v[94:95] op_sel_hi:[1,0,1]
	v_pk_fma_f32 v[124:125], v[124:125], v[130:131], v[92:93] op_sel_hi:[1,0,1]
	v_pk_fma_f32 v[122:123], v[122:123], v[130:131], v[90:91] op_sel_hi:[1,0,1]
	v_max_f32_e32 v120, 0, v120
	v_max_f32_e32 v121, 0, v121
	v_max_f32_e32 v124, 0, v124
	v_max_f32_e32 v125, 0, v125
	v_pk_mul_f32 v[132:133], v[120:121], v[120:121]
	v_max_f32_e32 v120, 0, v126
	v_max_f32_e32 v122, 0, v122
	v_max_f32_e32 v121, 0, v127
	v_max_f32_e32 v123, 0, v123
	v_pk_mul_f32 v[124:125], v[124:125], v[124:125]
	v_pk_mul_f32 v[126:127], v[120:121], v[120:121]
	v_pk_mul_f32 v[134:135], v[122:123], v[122:123]
	v_pk_fma_f32 v[112:113], v[112:113], v[130:131], v[80:81] op_sel_hi:[1,0,1]
	v_cvt_pk_bf16_f32 v120, v124, v125
	v_cvt_pk_bf16_f32 v121, v126, v127
	v_cvt_pk_bf16_f32 v122, v132, v133
	v_cvt_pk_bf16_f32 v123, v134, v135
	v_pk_fma_f32 v[118:119], v[118:119], v[130:131], v[86:87] op_sel_hi:[1,0,1]
	v_pk_fma_f32 v[116:117], v[116:117], v[130:131], v[84:85] op_sel_hi:[1,0,1]
	v_pk_fma_f32 v[114:115], v[114:115], v[130:131], v[82:83] op_sel_hi:[1,0,1]
	v_max_f32_e32 v112, 0, v112
	v_max_f32_e32 v113, 0, v113
	global_store_dwordx4 v[128:129], v[120:123], off
	v_max_f32_e32 v116, 0, v116
	v_max_f32_e32 v117, 0, v117
	v_pk_mul_f32 v[120:121], v[112:113], v[112:113]
	v_max_f32_e32 v112, 0, v118
	v_max_f32_e32 v114, 0, v114
	v_max_f32_e32 v113, 0, v119
	v_max_f32_e32 v115, 0, v115
	v_pk_mul_f32 v[116:117], v[116:117], v[116:117]
	v_pk_mul_f32 v[118:119], v[112:113], v[112:113]
	v_pk_mul_f32 v[122:123], v[114:115], v[114:115]
	v_cvt_pk_bf16_f32 v112, v116, v117
	v_cvt_pk_bf16_f32 v113, v118, v119
	v_cvt_pk_bf16_f32 v114, v120, v121
	v_cvt_pk_bf16_f32 v115, v122, v123
	global_store_dwordx4 v[128:129], v[112:115], off offset:256
	s_nop 1
	v_fmamk_f32 v114, v171, 0x3a800000, v228
	v_cmp_gt_f32_e32 vcc, s1, v114
	v_mul_f32_e32 v115, 0x4f800000, v114
	v_lshlrev_b64 v[112:113], 13, v[160:161]
	v_cndmask_b32_e32 v114, v114, v115, vcc
	v_sqrt_f32_e32 v115, v114
	v_lshl_add_u64 v[112:113], s[14:15], 0, v[112:113]
	v_lshl_add_u64 v[112:113], v[112:113], 0, v[158:159]
	v_add_u32_e32 v116, -1, v115
	v_fma_f32 v117, -v116, v115, v114
	v_cmp_ge_f32_e64 s[8:9], 0, v117
	v_add_u32_e32 v117, 1, v115
	s_nop 0
	v_cndmask_b32_e64 v116, v115, v116, s[8:9]
	v_fma_f32 v115, -v117, v115, v114
	v_cmp_lt_f32_e64 s[8:9], 0, v115
	s_nop 1
	v_cndmask_b32_e64 v115, v116, v117, s[8:9]
	v_mul_f32_e32 v116, 0x37800000, v115
	v_cndmask_b32_e32 v115, v115, v116, vcc
	v_cmp_class_f32_e32 vcc, v114, v229
	s_nop 1
	v_cndmask_b32_e32 v114, v115, v114, vcc
	v_div_scale_f32 v115, s[8:9], v114, v114, 1.0
	v_rcp_f32_e32 v116, v115
	s_nop 0
	v_fma_f32 v117, -v115, v116, 1.0
	v_fmac_f32_e32 v116, v117, v116
	v_div_scale_f32 v117, vcc, 1.0, v114, 1.0
	v_mul_f32_e32 v118, v117, v116
	v_fma_f32 v119, -v115, v118, v117
	v_fmac_f32_e32 v118, v119, v116
	v_fma_f32 v115, -v115, v118, v117
	v_div_fmas_f32 v115, v115, v116, v118
	v_div_fixup_f32 v114, v115, v114, 1.0
	v_pk_fma_f32 v[104:105], v[104:105], v[114:115], v[88:89] op_sel_hi:[1,0,1]
	v_pk_fma_f32 v[110:111], v[110:111], v[114:115], v[94:95] op_sel_hi:[1,0,1]
	v_pk_fma_f32 v[108:109], v[108:109], v[114:115], v[92:93] op_sel_hi:[1,0,1]
	v_pk_fma_f32 v[106:107], v[106:107], v[114:115], v[90:91] op_sel_hi:[1,0,1]
	v_max_f32_e32 v104, 0, v104
	v_max_f32_e32 v105, 0, v105
	v_max_f32_e32 v108, 0, v108
	v_max_f32_e32 v109, 0, v109
	v_pk_mul_f32 v[116:117], v[104:105], v[104:105]
	v_max_f32_e32 v104, 0, v110
	v_max_f32_e32 v106, 0, v106
	v_max_f32_e32 v105, 0, v111
	v_max_f32_e32 v107, 0, v107
	v_pk_mul_f32 v[108:109], v[108:109], v[108:109]
	v_pk_mul_f32 v[110:111], v[104:105], v[104:105]
	v_pk_mul_f32 v[118:119], v[106:107], v[106:107]
	v_pk_fma_f32 v[96:97], v[96:97], v[114:115], v[80:81] op_sel_hi:[1,0,1]
	v_cvt_pk_bf16_f32 v104, v108, v109
	v_cvt_pk_bf16_f32 v105, v110, v111
	v_cvt_pk_bf16_f32 v106, v116, v117
	v_cvt_pk_bf16_f32 v107, v118, v119
	v_pk_fma_f32 v[102:103], v[102:103], v[114:115], v[86:87] op_sel_hi:[1,0,1]
	v_pk_fma_f32 v[100:101], v[100:101], v[114:115], v[84:85] op_sel_hi:[1,0,1]
	v_pk_fma_f32 v[98:99], v[98:99], v[114:115], v[82:83] op_sel_hi:[1,0,1]
	v_max_f32_e32 v96, 0, v96
	v_max_f32_e32 v97, 0, v97
	global_store_dwordx4 v[112:113], v[104:107], off
	v_max_f32_e32 v100, 0, v100
	v_max_f32_e32 v101, 0, v101
	v_pk_mul_f32 v[104:105], v[96:97], v[96:97]
	v_max_f32_e32 v96, 0, v102
	v_max_f32_e32 v98, 0, v98
	v_max_f32_e32 v97, 0, v103
	v_max_f32_e32 v99, 0, v99
	v_pk_mul_f32 v[100:101], v[100:101], v[100:101]
	v_pk_mul_f32 v[102:103], v[96:97], v[96:97]
	v_pk_mul_f32 v[106:107], v[98:99], v[98:99]
	v_cvt_pk_bf16_f32 v96, v100, v101
	v_cvt_pk_bf16_f32 v97, v102, v103
	v_cvt_pk_bf16_f32 v98, v104, v105
	v_cvt_pk_bf16_f32 v99, v106, v107
	global_store_dwordx4 v[112:113], v[96:99], off offset:256
	s_nop 1
	v_fmamk_f32 v98, v170, 0x3a800000, v228
	v_cmp_gt_f32_e32 vcc, s1, v98
	v_mul_f32_e32 v99, 0x4f800000, v98
	v_lshlrev_b64 v[96:97], 13, v[156:157]
	v_cndmask_b32_e32 v98, v98, v99, vcc
	v_sqrt_f32_e32 v99, v98
	v_lshl_add_u64 v[96:97], s[14:15], 0, v[96:97]
	v_lshl_add_u64 v[96:97], v[96:97], 0, v[158:159]
	v_add_u32_e32 v100, -1, v99
	v_fma_f32 v101, -v100, v99, v98
	v_cmp_ge_f32_e64 s[8:9], 0, v101
	v_add_u32_e32 v101, 1, v99
	s_nop 0
	v_cndmask_b32_e64 v100, v99, v100, s[8:9]
	v_fma_f32 v99, -v101, v99, v98
	v_cmp_lt_f32_e64 s[8:9], 0, v99
	s_nop 1
	v_cndmask_b32_e64 v99, v100, v101, s[8:9]
	v_mul_f32_e32 v100, 0x37800000, v99
	v_cndmask_b32_e32 v99, v99, v100, vcc
	v_cmp_class_f32_e32 vcc, v98, v229
	s_nop 1
	v_cndmask_b32_e32 v98, v99, v98, vcc
	v_div_scale_f32 v99, s[8:9], v98, v98, 1.0
	v_rcp_f32_e32 v100, v99
	s_mov_b64 s[8:9], 0x100000
	v_fma_f32 v101, -v99, v100, 1.0
	v_fmac_f32_e32 v100, v101, v100
	v_div_scale_f32 v101, vcc, 1.0, v98, 1.0
	v_mul_f32_e32 v102, v101, v100
	v_fma_f32 v103, -v99, v102, v101
	v_fmac_f32_e32 v102, v103, v100
	v_fma_f32 v99, -v99, v102, v101
	v_div_fmas_f32 v99, v99, v100, v102
	v_div_fixup_f32 v98, v99, v98, 1.0
	v_pk_fma_f32 v[72:73], v[72:73], v[98:99], v[88:89] op_sel_hi:[1,0,1]
	v_pk_fma_f32 v[78:79], v[78:79], v[98:99], v[94:95] op_sel_hi:[1,0,1]
	v_pk_fma_f32 v[76:77], v[76:77], v[98:99], v[92:93] op_sel_hi:[1,0,1]
	v_pk_fma_f32 v[74:75], v[74:75], v[98:99], v[90:91] op_sel_hi:[1,0,1]
	v_max_f32_e32 v72, 0, v72
	v_max_f32_e32 v73, 0, v73
	v_max_f32_e32 v76, 0, v76
	v_max_f32_e32 v77, 0, v77
	v_pk_mul_f32 v[100:101], v[72:73], v[72:73]
	v_max_f32_e32 v72, 0, v78
	v_max_f32_e32 v74, 0, v74
	v_max_f32_e32 v73, 0, v79
	v_max_f32_e32 v75, 0, v75
	v_pk_mul_f32 v[76:77], v[76:77], v[76:77]
	v_pk_mul_f32 v[78:79], v[72:73], v[72:73]
	v_pk_mul_f32 v[102:103], v[74:75], v[74:75]
	v_pk_fma_f32 v[64:65], v[64:65], v[98:99], v[80:81] op_sel_hi:[1,0,1]
	v_cvt_pk_bf16_f32 v72, v76, v77
	v_cvt_pk_bf16_f32 v73, v78, v79
	v_cvt_pk_bf16_f32 v74, v100, v101
	v_cvt_pk_bf16_f32 v75, v102, v103
	v_pk_fma_f32 v[70:71], v[70:71], v[98:99], v[86:87] op_sel_hi:[1,0,1]
	v_pk_fma_f32 v[68:69], v[68:69], v[98:99], v[84:85] op_sel_hi:[1,0,1]
	v_pk_fma_f32 v[66:67], v[66:67], v[98:99], v[82:83] op_sel_hi:[1,0,1]
	v_max_f32_e32 v64, 0, v64
	v_max_f32_e32 v65, 0, v65
	global_store_dwordx4 v[96:97], v[72:75], off
	v_max_f32_e32 v68, 0, v68
	v_max_f32_e32 v69, 0, v69
	v_pk_mul_f32 v[72:73], v[64:65], v[64:65]
	v_max_f32_e32 v64, 0, v70
	v_max_f32_e32 v66, 0, v66
	v_max_f32_e32 v65, 0, v71
	v_max_f32_e32 v67, 0, v67
	v_pk_mul_f32 v[68:69], v[68:69], v[68:69]
	v_pk_mul_f32 v[70:71], v[64:65], v[64:65]
	v_pk_mul_f32 v[74:75], v[66:67], v[66:67]
	v_cvt_pk_bf16_f32 v64, v68, v69
	v_cvt_pk_bf16_f32 v65, v70, v71
	v_cvt_pk_bf16_f32 v66, v72, v73
	v_cvt_pk_bf16_f32 v67, v74, v75
	global_store_dwordx4 v[96:97], v[64:67], off offset:256
	s_nop 1
	v_fmamk_f32 v66, v169, 0x3a800000, v228
	v_cmp_gt_f32_e32 vcc, s1, v66
	v_mul_f32_e32 v67, 0x4f800000, v66
	v_lshl_add_u64 v[64:65], v[154:155], 0, s[8:9]
	v_cndmask_b32_e32 v66, v66, v67, vcc
	v_sqrt_f32_e32 v67, v66
	s_nop 0
	v_add_u32_e32 v68, -1, v67
	v_fma_f32 v69, -v68, v67, v66
	v_cmp_ge_f32_e64 s[8:9], 0, v69
	v_add_u32_e32 v69, 1, v67
	s_nop 0
	v_cndmask_b32_e64 v68, v67, v68, s[8:9]
	v_fma_f32 v67, -v69, v67, v66
	v_cmp_lt_f32_e64 s[8:9], 0, v67
	s_nop 1
	v_cndmask_b32_e64 v67, v68, v69, s[8:9]
	v_mul_f32_e32 v68, 0x37800000, v67
	v_cndmask_b32_e32 v67, v67, v68, vcc
	v_cmp_class_f32_e32 vcc, v66, v229
	s_nop 1
	v_cndmask_b32_e32 v66, v67, v66, vcc
	v_div_scale_f32 v67, s[8:9], v66, v66, 1.0
	v_rcp_f32_e32 v68, v67
	s_mov_b32 s8, 0x100000
	v_fma_f32 v69, -v67, v68, 1.0
	v_fmac_f32_e32 v68, v69, v68
	v_div_scale_f32 v69, vcc, 1.0, v66, 1.0
	v_mul_f32_e32 v70, v69, v68
	v_fma_f32 v71, -v67, v70, v69
	v_fmac_f32_e32 v70, v71, v68
	v_fma_f32 v67, -v67, v70, v69
	v_div_fmas_f32 v67, v67, v68, v70
	v_div_fixup_f32 v66, v67, v66, 1.0
	v_pk_fma_f32 v[60:61], v[60:61], v[66:67], v[92:93] op_sel_hi:[1,0,1]
	v_pk_fma_f32 v[56:57], v[56:57], v[66:67], v[88:89] op_sel_hi:[1,0,1]
	v_pk_fma_f32 v[62:63], v[62:63], v[66:67], v[94:95] op_sel_hi:[1,0,1]
	v_pk_fma_f32 v[58:59], v[58:59], v[66:67], v[90:91] op_sel_hi:[1,0,1]
	v_max_f32_e32 v60, 0, v60
	v_max_f32_e32 v56, 0, v56
	v_max_f32_e32 v61, 0, v61
	v_max_f32_e32 v57, 0, v57
	v_pk_mul_f32 v[60:61], v[60:61], v[60:61]
	v_pk_mul_f32 v[68:69], v[56:57], v[56:57]
	v_max_f32_e32 v56, 0, v62
	v_max_f32_e32 v58, 0, v58
	v_max_f32_e32 v57, 0, v63
	v_max_f32_e32 v59, 0, v59
	v_pk_mul_f32 v[62:63], v[56:57], v[56:57]
	v_pk_mul_f32 v[70:71], v[58:59], v[58:59]
	v_cvt_pk_bf16_f32 v56, v60, v61
	v_add_co_u32_e32 v60, vcc, s8, v154
	v_pk_fma_f32 v[48:49], v[48:49], v[66:67], v[80:81] op_sel_hi:[1,0,1]
	v_cvt_pk_bf16_f32 v57, v62, v63
	v_cvt_pk_bf16_f32 v58, v68, v69
	v_cvt_pk_bf16_f32 v59, v70, v71
	v_addc_co_u32_e32 v61, vcc, 0, v155, vcc
	v_pk_fma_f32 v[54:55], v[54:55], v[66:67], v[86:87] op_sel_hi:[1,0,1]
	v_pk_fma_f32 v[52:53], v[52:53], v[66:67], v[84:85] op_sel_hi:[1,0,1]
	v_pk_fma_f32 v[50:51], v[50:51], v[66:67], v[82:83] op_sel_hi:[1,0,1]
	v_max_f32_e32 v48, 0, v48
	v_max_f32_e32 v49, 0, v49
	global_store_dwordx4 v[60:61], v[56:59], off
	v_max_f32_e32 v52, 0, v52
	v_max_f32_e32 v53, 0, v53
	v_pk_mul_f32 v[56:57], v[48:49], v[48:49]
	v_max_f32_e32 v48, 0, v54
	v_max_f32_e32 v50, 0, v50
	v_max_f32_e32 v49, 0, v55
	v_max_f32_e32 v51, 0, v51
	v_pk_mul_f32 v[52:53], v[52:53], v[52:53]
	v_pk_mul_f32 v[54:55], v[48:49], v[48:49]
	v_pk_mul_f32 v[58:59], v[50:51], v[50:51]
	v_cvt_pk_bf16_f32 v48, v52, v53
	v_cvt_pk_bf16_f32 v49, v54, v55
	v_cvt_pk_bf16_f32 v50, v56, v57
	v_cvt_pk_bf16_f32 v51, v58, v59
	global_store_dwordx4 v[64:65], v[48:51], off offset:256
	s_mov_b64 s[8:9], 0x120000
	s_nop 0
	v_fmamk_f32 v50, v168, 0x3a800000, v228
	v_cmp_gt_f32_e32 vcc, s1, v50
	v_mul_f32_e32 v51, 0x4f800000, v50
	v_lshl_add_u64 v[48:49], v[154:155], 0, s[8:9]
	v_cndmask_b32_e32 v50, v50, v51, vcc
	v_sqrt_f32_e32 v51, v50
	s_nop 0
	v_add_u32_e32 v52, -1, v51
	v_fma_f32 v53, -v52, v51, v50
	v_cmp_ge_f32_e64 s[8:9], 0, v53
	v_add_u32_e32 v53, 1, v51
	s_nop 0
	v_cndmask_b32_e64 v52, v51, v52, s[8:9]
	v_fma_f32 v51, -v53, v51, v50
	v_cmp_lt_f32_e64 s[8:9], 0, v51
	s_nop 1
	v_cndmask_b32_e64 v51, v52, v53, s[8:9]
	v_mul_f32_e32 v52, 0x37800000, v51
	v_cndmask_b32_e32 v51, v51, v52, vcc
	v_cmp_class_f32_e32 vcc, v50, v229
	s_nop 1
	v_cndmask_b32_e32 v50, v51, v50, vcc
	v_div_scale_f32 v51, s[8:9], v50, v50, 1.0
	v_rcp_f32_e32 v52, v51
	s_mov_b32 s8, 0x120000
	v_fma_f32 v53, -v51, v52, 1.0
	v_fmac_f32_e32 v52, v53, v52
	v_div_scale_f32 v53, vcc, 1.0, v50, 1.0
	v_mul_f32_e32 v54, v53, v52
	v_fma_f32 v55, -v51, v54, v53
	v_fmac_f32_e32 v54, v55, v52
	v_fma_f32 v51, -v51, v54, v53
	v_div_fmas_f32 v51, v51, v52, v54
	v_div_fixup_f32 v50, v51, v50, 1.0
	v_pk_fma_f32 v[44:45], v[44:45], v[50:51], v[92:93] op_sel_hi:[1,0,1]
	v_pk_fma_f32 v[40:41], v[40:41], v[50:51], v[88:89] op_sel_hi:[1,0,1]
	v_pk_fma_f32 v[46:47], v[46:47], v[50:51], v[94:95] op_sel_hi:[1,0,1]
	v_pk_fma_f32 v[42:43], v[42:43], v[50:51], v[90:91] op_sel_hi:[1,0,1]
	v_max_f32_e32 v44, 0, v44
	v_max_f32_e32 v40, 0, v40
	v_max_f32_e32 v45, 0, v45
	v_max_f32_e32 v41, 0, v41
	v_pk_mul_f32 v[44:45], v[44:45], v[44:45]
	v_pk_mul_f32 v[52:53], v[40:41], v[40:41]
	v_max_f32_e32 v40, 0, v46
	v_max_f32_e32 v42, 0, v42
	v_max_f32_e32 v41, 0, v47
	v_max_f32_e32 v43, 0, v43
	v_pk_mul_f32 v[46:47], v[40:41], v[40:41]
	v_pk_mul_f32 v[54:55], v[42:43], v[42:43]
	v_cvt_pk_bf16_f32 v40, v44, v45
	v_add_co_u32_e32 v44, vcc, s8, v154
	v_pk_fma_f32 v[32:33], v[32:33], v[50:51], v[80:81] op_sel_hi:[1,0,1]
	v_cvt_pk_bf16_f32 v41, v46, v47
	v_cvt_pk_bf16_f32 v42, v52, v53
	v_cvt_pk_bf16_f32 v43, v54, v55
	v_addc_co_u32_e32 v45, vcc, 0, v155, vcc
	v_pk_fma_f32 v[38:39], v[38:39], v[50:51], v[86:87] op_sel_hi:[1,0,1]
	v_pk_fma_f32 v[36:37], v[36:37], v[50:51], v[84:85] op_sel_hi:[1,0,1]
	v_pk_fma_f32 v[34:35], v[34:35], v[50:51], v[82:83] op_sel_hi:[1,0,1]
	v_max_f32_e32 v32, 0, v32
	v_max_f32_e32 v33, 0, v33
	global_store_dwordx4 v[44:45], v[40:43], off
	v_max_f32_e32 v36, 0, v36
	v_max_f32_e32 v37, 0, v37
	v_pk_mul_f32 v[40:41], v[32:33], v[32:33]
	v_max_f32_e32 v32, 0, v38
	v_max_f32_e32 v34, 0, v34
	v_max_f32_e32 v33, 0, v39
	v_max_f32_e32 v35, 0, v35
	v_pk_mul_f32 v[36:37], v[36:37], v[36:37]
	v_pk_mul_f32 v[38:39], v[32:33], v[32:33]
	v_pk_mul_f32 v[42:43], v[34:35], v[34:35]
	v_cvt_pk_bf16_f32 v32, v36, v37
	v_cvt_pk_bf16_f32 v33, v38, v39
	v_cvt_pk_bf16_f32 v34, v40, v41
	v_cvt_pk_bf16_f32 v35, v42, v43
	global_store_dwordx4 v[48:49], v[32:35], off offset:256
	s_mov_b64 s[8:9], 0x140000
	s_nop 0
	v_fmamk_f32 v34, v167, 0x3a800000, v228
	v_cmp_gt_f32_e32 vcc, s1, v34
	v_mul_f32_e32 v35, 0x4f800000, v34
	v_lshl_add_u64 v[32:33], v[154:155], 0, s[8:9]
	v_cndmask_b32_e32 v34, v34, v35, vcc
	v_sqrt_f32_e32 v35, v34
	s_nop 0
	v_add_u32_e32 v36, -1, v35
	v_fma_f32 v37, -v36, v35, v34
	v_cmp_ge_f32_e64 s[8:9], 0, v37
	v_add_u32_e32 v37, 1, v35
	s_nop 0
	v_cndmask_b32_e64 v36, v35, v36, s[8:9]
	v_fma_f32 v35, -v37, v35, v34
	v_cmp_lt_f32_e64 s[8:9], 0, v35
	s_nop 1
	v_cndmask_b32_e64 v35, v36, v37, s[8:9]
	v_mul_f32_e32 v36, 0x37800000, v35
	v_cndmask_b32_e32 v35, v35, v36, vcc
	v_cmp_class_f32_e32 vcc, v34, v229
	s_nop 1
	v_cndmask_b32_e32 v34, v35, v34, vcc
	v_div_scale_f32 v35, s[8:9], v34, v34, 1.0
	v_rcp_f32_e32 v36, v35
	s_mov_b32 s8, 0x140000
	v_fma_f32 v37, -v35, v36, 1.0
	v_fmac_f32_e32 v36, v37, v36
	v_div_scale_f32 v37, vcc, 1.0, v34, 1.0
	v_mul_f32_e32 v38, v37, v36
	v_fma_f32 v39, -v35, v38, v37
	v_fmac_f32_e32 v38, v39, v36
	v_fma_f32 v35, -v35, v38, v37
	v_div_fmas_f32 v35, v35, v36, v38
	v_div_fixup_f32 v34, v35, v34, 1.0
	v_pk_fma_f32 v[28:29], v[28:29], v[34:35], v[92:93] op_sel_hi:[1,0,1]
	v_pk_fma_f32 v[24:25], v[24:25], v[34:35], v[88:89] op_sel_hi:[1,0,1]
	v_pk_fma_f32 v[30:31], v[30:31], v[34:35], v[94:95] op_sel_hi:[1,0,1]
	v_pk_fma_f32 v[26:27], v[26:27], v[34:35], v[90:91] op_sel_hi:[1,0,1]
	v_max_f32_e32 v28, 0, v28
	v_max_f32_e32 v24, 0, v24
	v_max_f32_e32 v29, 0, v29
	v_max_f32_e32 v25, 0, v25
	v_pk_mul_f32 v[28:29], v[28:29], v[28:29]
	v_pk_mul_f32 v[36:37], v[24:25], v[24:25]
	v_max_f32_e32 v24, 0, v30
	v_max_f32_e32 v26, 0, v26
	v_max_f32_e32 v25, 0, v31
	v_max_f32_e32 v27, 0, v27
	v_pk_mul_f32 v[30:31], v[24:25], v[24:25]
	v_pk_mul_f32 v[38:39], v[26:27], v[26:27]
	v_cvt_pk_bf16_f32 v24, v28, v29
	v_add_co_u32_e32 v28, vcc, s8, v154
	v_pk_fma_f32 v[16:17], v[16:17], v[34:35], v[80:81] op_sel_hi:[1,0,1]
	v_cvt_pk_bf16_f32 v25, v30, v31
	v_cvt_pk_bf16_f32 v26, v36, v37
	v_cvt_pk_bf16_f32 v27, v38, v39
	v_addc_co_u32_e32 v29, vcc, 0, v155, vcc
	v_pk_fma_f32 v[22:23], v[22:23], v[34:35], v[86:87] op_sel_hi:[1,0,1]
	v_pk_fma_f32 v[20:21], v[20:21], v[34:35], v[84:85] op_sel_hi:[1,0,1]
	v_pk_fma_f32 v[18:19], v[18:19], v[34:35], v[82:83] op_sel_hi:[1,0,1]
	v_max_f32_e32 v16, 0, v16
	v_max_f32_e32 v17, 0, v17
	global_store_dwordx4 v[28:29], v[24:27], off
	v_max_f32_e32 v20, 0, v20
	v_max_f32_e32 v21, 0, v21
	v_pk_mul_f32 v[24:25], v[16:17], v[16:17]
	v_max_f32_e32 v16, 0, v22
	v_max_f32_e32 v18, 0, v18
	v_max_f32_e32 v17, 0, v23
	v_max_f32_e32 v19, 0, v19
	v_pk_mul_f32 v[20:21], v[20:21], v[20:21]
	v_pk_mul_f32 v[22:23], v[16:17], v[16:17]
	v_pk_mul_f32 v[26:27], v[18:19], v[18:19]
	v_cvt_pk_bf16_f32 v16, v20, v21
	v_cvt_pk_bf16_f32 v17, v22, v23
	v_cvt_pk_bf16_f32 v18, v24, v25
	v_cvt_pk_bf16_f32 v19, v26, v27
	global_store_dwordx4 v[32:33], v[16:19], off offset:256
	s_mov_b64 s[8:9], 0x160000
	s_nop 0
	v_fmamk_f32 v18, v166, 0x3a800000, v228
	v_cmp_gt_f32_e32 vcc, s1, v18
	v_mul_f32_e32 v19, 0x4f800000, v18
	v_lshl_add_u64 v[16:17], v[154:155], 0, s[8:9]
	v_cndmask_b32_e32 v18, v18, v19, vcc
	v_sqrt_f32_e32 v19, v18
	s_nop 0
	v_add_u32_e32 v20, -1, v19
	v_fma_f32 v21, -v20, v19, v18
	v_cmp_ge_f32_e64 s[8:9], 0, v21
	v_add_u32_e32 v21, 1, v19
	s_nop 0
	v_cndmask_b32_e64 v20, v19, v20, s[8:9]
	v_fma_f32 v19, -v21, v19, v18
	v_cmp_lt_f32_e64 s[8:9], 0, v19
	s_nop 1
	v_cndmask_b32_e64 v19, v20, v21, s[8:9]
	v_mul_f32_e32 v20, 0x37800000, v19
	v_cndmask_b32_e32 v19, v19, v20, vcc
	v_cmp_class_f32_e32 vcc, v18, v229
	s_nop 1
	v_cndmask_b32_e32 v18, v19, v18, vcc
	v_div_scale_f32 v19, s[8:9], v18, v18, 1.0
	v_rcp_f32_e32 v20, v19
	s_mov_b32 s8, 0x160000
	v_fma_f32 v21, -v19, v20, 1.0
	v_fmac_f32_e32 v20, v21, v20
	v_div_scale_f32 v21, vcc, 1.0, v18, 1.0
	v_mul_f32_e32 v22, v21, v20
	v_fma_f32 v23, -v19, v22, v21
	v_fmac_f32_e32 v22, v23, v20
	v_fma_f32 v19, -v19, v22, v21
	v_div_fmas_f32 v19, v19, v20, v22
	v_div_fixup_f32 v18, v19, v18, 1.0
	v_pk_fma_f32 v[12:13], v[12:13], v[18:19], v[92:93] op_sel_hi:[1,0,1]
	v_pk_fma_f32 v[8:9], v[8:9], v[18:19], v[88:89] op_sel_hi:[1,0,1]
	v_pk_fma_f32 v[14:15], v[14:15], v[18:19], v[94:95] op_sel_hi:[1,0,1]
	v_pk_fma_f32 v[10:11], v[10:11], v[18:19], v[90:91] op_sel_hi:[1,0,1]
	v_max_f32_e32 v12, 0, v12
	v_max_f32_e32 v8, 0, v8
	v_max_f32_e32 v13, 0, v13
	v_max_f32_e32 v9, 0, v9
	v_pk_mul_f32 v[12:13], v[12:13], v[12:13]
	v_pk_mul_f32 v[20:21], v[8:9], v[8:9]
	v_max_f32_e32 v8, 0, v14
	v_max_f32_e32 v10, 0, v10
	v_max_f32_e32 v9, 0, v15
	v_max_f32_e32 v11, 0, v11
	v_pk_mul_f32 v[14:15], v[8:9], v[8:9]
	v_pk_mul_f32 v[22:23], v[10:11], v[10:11]
	v_cvt_pk_bf16_f32 v8, v12, v13
	v_add_co_u32_e32 v12, vcc, s8, v154
	v_pk_fma_f32 v[0:1], v[0:1], v[18:19], v[80:81] op_sel_hi:[1,0,1]
	v_cvt_pk_bf16_f32 v9, v14, v15
	v_cvt_pk_bf16_f32 v10, v20, v21
	v_cvt_pk_bf16_f32 v11, v22, v23
	v_addc_co_u32_e32 v13, vcc, 0, v155, vcc
	v_pk_fma_f32 v[6:7], v[6:7], v[18:19], v[86:87] op_sel_hi:[1,0,1]
	v_pk_fma_f32 v[4:5], v[4:5], v[18:19], v[84:85] op_sel_hi:[1,0,1]
	v_pk_fma_f32 v[2:3], v[2:3], v[18:19], v[82:83] op_sel_hi:[1,0,1]
	v_max_f32_e32 v0, 0, v0
	v_max_f32_e32 v1, 0, v1
	global_store_dwordx4 v[12:13], v[8:11], off
	v_max_f32_e32 v4, 0, v4
	v_max_f32_e32 v5, 0, v5
	v_pk_mul_f32 v[8:9], v[0:1], v[0:1]
	v_max_f32_e32 v0, 0, v6
	v_max_f32_e32 v2, 0, v2
	v_max_f32_e32 v1, 0, v7
	v_max_f32_e32 v3, 0, v3
	v_pk_mul_f32 v[4:5], v[4:5], v[4:5]
	v_pk_mul_f32 v[6:7], v[0:1], v[0:1]
	v_pk_mul_f32 v[10:11], v[2:3], v[2:3]
	v_cvt_pk_bf16_f32 v0, v4, v5
	v_cvt_pk_bf16_f32 v1, v6, v7
	v_cvt_pk_bf16_f32 v2, v8, v9
	v_cvt_pk_bf16_f32 v3, v10, v11
	s_mov_b64 s[8:9], -1
	s_andn2_b64 vcc, exec, s[6:7]
	global_store_dwordx4 v[16:17], v[0:3], off offset:256
	s_cbranch_vccnz .LBB0_1296
	s_andn2_b64 vcc, exec, s[10:11]
	s_cbranch_vccnz .LBB0_1295
	s_barrier
	s_branch .LBB0_1295
